# wo GEMM of the attention layer: f32 residual added into the f32 accumulators during the K loop (one row block per pass, requested a pass ahead); epilogue only converts and stores
# speedup vs baseline: 1.0834x; 1.0038x over previous
; #define PG8_WAIT_V(n) asm volatile("s_waitcnt vmcnt(" #n ")" ::: "memory")
; template <class Epi, class Sched, bool ALIGN_EPI = false, bool SP2 = false>
; __device__ __forceinline__ void gemm_phase(PG8_LAS unsigned char* lds, const Gemm g, const Sched& S, const Epi& E, const int tid_in) {
;     ...
;     f32x4 acc[2][2][4][2];
; #pragma unroll
;     for (int a = 0; a < 2; ++a)
; #pragma unroll
;         for (int b = 0; b < 2; ++b)
; #pragma unroll
;             for (int m = 0; m < 4; ++m)
; #pragma unroll
;                 for (int n = 0; n < 2; ++n) acc[a][b][m][n] = (f32x4){0.f, 0.f, 0.f, 0.f};
;     bf16x8 At[4][2], B0[2][2], B1[2][2];
;     const char* cA = (const char*)g.asel(cur.pn) + (size_t)cur.pm * tstep; const char* cB = (const char*)g.Bt + (size_t)cur.pn * tstep;
;     S.a_ready(cur);
;     if constexpr (SP2) {
;         PG8_STAGE(PG8_SB(0, 0), cB, voffB); PG8_STAGE(PG8_SB(0, 1), cB + hstep, voffB); PG8_STAGE(PG8_SA(0, 0), cA, voffA); PG8_STAGE(PG8_SA(0, 1), cA + hstep, voffA);
;         if (wr == 1) PG8_BAR;
;         PG8_WAIT_V(2); PG8_BAR;
;         PG8_STAGE(PG8_SB(1, 0), cB + kstep, voffB); PG8_STAGE(PG8_SA(1, 0), cA + kstep, voffA); PG8_STAGE(PG8_SB(1, 1), cB + hstep + kstep, voffB);
;         PG8_WAIT_V(6); PG8_BAR;
;     } else {
;         PG8_STAGE(PG8_SB(0, 0), cB, voffB); PG8_STAGE(PG8_SA(0, 0), cA, voffA); PG8_STAGE(PG8_SB(0, 1), cB + hstep, voffB); PG8_STAGE(PG8_SA(0, 1), cA + hstep, voffA);
;         if (wr == 1) PG8_BAR;
;         PG8_WAIT_V(4); PG8_BAR;
;         PG8_STAGE(PG8_SB(1, 0), cB + kstep, voffB); PG8_STAGE(PG8_SA(1, 0), cA + kstep, voffA); PG8_STAGE(PG8_SB(1, 1), cB + hstep + kstep, voffB);
;         PG8_WAIT_V(6); PG8_BAR;
;     }
;     for (;;) {
;         const bool has_next = S.next(ui + 1, nxt);
;         const char* nA = has_next ? (const char*)g.asel(nxt.pn) + (size_t)nxt.pm * tstep : cA; const char* nB = has_next ? (const char*)g.Bt + (size_t)nxt.pn * tstep : cB;
;         for (int t = 0; t < nt; t += 2) {
;             const bool last = (t == nt - 2);
;             const char* a1 = cA + (size_t)(t + 1) * kstep;
;             const char* a2 = last ? nA : cA + (size_t)(t + 2) * kstep; const char* b2 = last ? nB : cB + (size_t)(t + 2) * kstep;
;             const char* a3 = a2 + kstep; const char* b3 = b2 + kstep;
;             if (last && has_next) S.a_ready(nxt);
;             if constexpr (SP2) {
.LBB0_315:
	s_ashr_i32 s27, s26, 31
	s_lshl_b64 s[28:29], s[26:27], 19
	s_add_u32 s28, s33, s28
	s_addc_u32 s29, s40, s29
	s_and_b64 s[30:31], s[2:3], exec
	s_cselect_b32 s27, s29, s1
	s_cselect_b32 s58, s28, s0
	s_ashr_i32 s25, s24, 31
	s_lshl_b64 s[30:31], s[24:25], 19
	s_add_u32 s30, s41, s30
	s_addc_u32 s31, s42, s31
	s_and_b64 s[38:39], s[2:3], exec
	s_cselect_b32 s25, s31, s37
	s_cselect_b32 s59, s30, s36
	s_add_u32 s0, s0, 0x40080
	s_addc_u32 s1, s1, 0
	s_add_u32 s60, s36, 0x100
	v_mov_b32_e32 v0, 0
	s_addc_u32 s61, s37, 0
	s_mov_b32 s62, -2
	v_mov_b32_e32 v1, v0
	v_mov_b32_e32 v2, v0
	v_mov_b32_e32 v3, v0
	v_mov_b32_e32 v4, v0
	v_mov_b32_e32 v5, v0
	v_mov_b32_e32 v6, v0
	v_mov_b32_e32 v7, v0
	v_mov_b32_e32 v16, v0
	v_mov_b32_e32 v17, v0
	v_mov_b32_e32 v18, v0
	v_mov_b32_e32 v19, v0
	v_mov_b32_e32 v20, v0
	v_mov_b32_e32 v21, v0
	v_mov_b32_e32 v22, v0
	v_mov_b32_e32 v23, v0
	v_mov_b32_e32 v32, v0
	v_mov_b32_e32 v33, v0
	v_mov_b32_e32 v34, v0
	v_mov_b32_e32 v35, v0
	v_mov_b32_e32 v36, v0
	v_mov_b32_e32 v37, v0
	v_mov_b32_e32 v38, v0
	v_mov_b32_e32 v39, v0
	v_mov_b32_e32 v48, v0
	v_mov_b32_e32 v49, v0
	v_mov_b32_e32 v50, v0
	v_mov_b32_e32 v51, v0
	v_mov_b32_e32 v52, v0
	v_mov_b32_e32 v53, v0
	v_mov_b32_e32 v54, v0
	v_mov_b32_e32 v55, v0
	v_mov_b32_e32 v8, v0
	v_mov_b32_e32 v9, v0
	v_mov_b32_e32 v10, v0
	v_mov_b32_e32 v11, v0
	v_mov_b32_e32 v12, v0
	v_mov_b32_e32 v13, v0
	v_mov_b32_e32 v14, v0
	v_mov_b32_e32 v15, v0
	v_mov_b32_e32 v24, v0
	v_mov_b32_e32 v25, v0
	v_mov_b32_e32 v26, v0
	v_mov_b32_e32 v27, v0
	v_mov_b32_e32 v28, v0
	v_mov_b32_e32 v29, v0
	v_mov_b32_e32 v30, v0
	v_mov_b32_e32 v31, v0
	v_mov_b32_e32 v40, v0
	v_mov_b32_e32 v41, v0
	v_mov_b32_e32 v42, v0
	v_mov_b32_e32 v43, v0
	v_mov_b32_e32 v44, v0
	v_mov_b32_e32 v45, v0
	v_mov_b32_e32 v46, v0
	v_mov_b32_e32 v47, v0
	v_mov_b32_e32 v56, v0
	v_mov_b32_e32 v57, v0
	v_mov_b32_e32 v58, v0
	v_mov_b32_e32 v59, v0
	v_mov_b32_e32 v60, v0
	v_mov_b32_e32 v61, v0
	v_mov_b32_e32 v62, v0
	v_mov_b32_e32 v63, v0
	v_mov_b32_e32 v64, v0
	v_mov_b32_e32 v65, v0
	v_mov_b32_e32 v66, v0
	v_mov_b32_e32 v67, v0
	v_mov_b32_e32 v68, v0
	v_mov_b32_e32 v69, v0
	v_mov_b32_e32 v70, v0
	v_mov_b32_e32 v71, v0
	v_mov_b32_e32 v80, v0
	v_mov_b32_e32 v81, v0
	v_mov_b32_e32 v82, v0
	v_mov_b32_e32 v83, v0
	v_mov_b32_e32 v84, v0
	v_mov_b32_e32 v85, v0
	v_mov_b32_e32 v86, v0
	v_mov_b32_e32 v87, v0
	v_mov_b32_e32 v96, v0
	v_mov_b32_e32 v97, v0
	v_mov_b32_e32 v98, v0
	v_mov_b32_e32 v99, v0
	v_mov_b32_e32 v100, v0
	v_mov_b32_e32 v101, v0
	v_mov_b32_e32 v102, v0
	v_mov_b32_e32 v103, v0
	v_mov_b32_e32 v112, v0
	v_mov_b32_e32 v113, v0
	v_mov_b32_e32 v114, v0
	v_mov_b32_e32 v115, v0
	v_mov_b32_e32 v116, v0
	v_mov_b32_e32 v117, v0
	v_mov_b32_e32 v118, v0
	v_mov_b32_e32 v119, v0
	v_mov_b32_e32 v72, v0
	v_mov_b32_e32 v73, v0
	v_mov_b32_e32 v74, v0
	v_mov_b32_e32 v75, v0
	v_mov_b32_e32 v76, v0
	v_mov_b32_e32 v77, v0
	v_mov_b32_e32 v78, v0
	v_mov_b32_e32 v79, v0
	v_mov_b32_e32 v88, v0
	v_mov_b32_e32 v89, v0
	v_mov_b32_e32 v90, v0
	v_mov_b32_e32 v91, v0
	v_mov_b32_e32 v92, v0
	v_mov_b32_e32 v93, v0
	v_mov_b32_e32 v94, v0
	v_mov_b32_e32 v95, v0
	v_mov_b32_e32 v104, v0
	v_mov_b32_e32 v105, v0
	v_mov_b32_e32 v106, v0
	v_mov_b32_e32 v107, v0
	v_mov_b32_e32 v108, v0
	v_mov_b32_e32 v109, v0
	v_mov_b32_e32 v110, v0
	v_mov_b32_e32 v111, v0
	v_mov_b32_e32 v120, v0
	v_mov_b32_e32 v121, v0
	v_mov_b32_e32 v122, v0
	v_mov_b32_e32 v123, v0
	v_mov_b32_e32 v124, v0
	v_mov_b32_e32 v125, v0
	v_mov_b32_e32 v126, v0
	v_mov_b32_e32 v127, v0
	v_lshl_add_u32 v224, s34, 8, v150
	v_lshl_or_b32 v226, s57, 8, v152
	v_ashrrev_i32_e32 v225, 31, v224
	v_ashrrev_i32_e32 v227, 31, v226
	v_lshlrev_b64 v[224:225], 10, v[224:225]
	v_lshl_add_u64 v[224:225], v[224:225], 0, v[226:227]
	v_lshl_add_u64 v[224:225], v[224:225], 2, s[6:7]
.LBB0_316:
	ds_read_b128 v[144:147], v153
	ds_read_b128 v[156:159], v153 offset:1024
	ds_read_b128 v[160:163], v153 offset:2048
	ds_read_b128 v[164:167], v153 offset:3072
	ds_read_b128 v[168:171], v154
	ds_read_b128 v[172:175], v154 offset:1024
	ds_read_b128 v[176:179], v154 offset:2048
	ds_read_b128 v[180:183], v154 offset:3072
	s_add_u32 s36, s0, 0xfffc0080
	s_addc_u32 s37, s1, -1
	s_cmp_eq_u32 s62, 12
	s_cselect_b32 s39, s27, s37
	s_cselect_b32 s38, s58, s36
	s_cselect_b32 s37, s25, s61
	s_cselect_b32 s36, s59, s60
	v_lshl_add_u64 v[148:149], s[0:1], 0, v[136:137]
	s_add_i32 m0, s35, 0xc000
	ds_read_b128 v[184:187], v155
	ds_read_b128 v[188:191], v155 offset:1024
	ds_read_b128 v[192:195], v155 offset:2048
	ds_read_b128 v[196:199], v155 offset:3072
	ds_read_b128 v[200:203], v155 offset:4096
	ds_read_b128 v[204:207], v155 offset:5120
	ds_read_b128 v[208:211], v155 offset:6144
	ds_read_b128 v[212:215], v155 offset:7168
	global_load_lds_dwordx4 v[148:149], off
	v_lshl_add_u64 v[148:149], s[0:1], 0, v[138:139]
	s_add_i32 m0, s35, 0xe000
	s_nop 0
	global_load_lds_dwordx4 v[148:149], off
	s_waitcnt vmcnt(8)
	s_waitcnt lgkmcnt(0)
	s_cmp_lt_i32 s62, 0
	s_cbranch_scc1 .Lmy_ra_done
	s_cmp_eq_u32 s62, 2
	s_cbranch_scc1 .Lmy_ra_1
	s_cmp_eq_u32 s62, 4
	s_cbranch_scc1 .Lmy_ra_2
	s_cmp_eq_u32 s62, 6
	s_cbranch_scc1 .Lmy_ra_3
	s_cmp_eq_u32 s62, 8
	s_cbranch_scc1 .Lmy_ra_4
	s_cmp_eq_u32 s62, 10
	s_cbranch_scc1 .Lmy_ra_5
	s_cmp_eq_u32 s62, 12
	s_cbranch_scc1 .Lmy_ra_6
	v_pk_add_f32 v[124:125], v[124:125], v[228:229]
	v_pk_add_f32 v[126:127], v[126:127], v[230:231]
	v_pk_add_f32 v[120:121], v[120:121], v[232:233]
	v_pk_add_f32 v[122:123], v[122:123], v[234:235]
	v_pk_add_f32 v[116:117], v[116:117], v[236:237]
	v_pk_add_f32 v[118:119], v[118:119], v[238:239]
	v_pk_add_f32 v[112:113], v[112:113], v[240:241]
	v_pk_add_f32 v[114:115], v[114:115], v[242:243]
	s_branch .Lmy_ra_done
; __device__ __forceinline__ u32x4 pack8(const f32x4 a, const f32x4 b) { u32x4 w; w.x = cvt_pk_bf16(a[0], a[1]); w.y = cvt_pk_bf16(a[2], a[3]); w.z = cvt_pk_bf16(b[0], b[1]); w.w = cvt_pk_bf16(b[2], b[3]); return w; }
; __device__ __forceinline__ void unpack8(const u32x4 w, f32x4& a, f32x4& b) { a = (f32x4){bflo(w.x), bfhi(w.x), bflo(w.y), bfhi(w.y)}; b = (f32x4){bflo(w.z), bfhi(w.z), bflo(w.w), bfhi(w.w)}; }
; #define PG8_STAGE(bufoff, gbase, voff) do { _Pragma("unroll") for (int _i = 0; _i < 2; ++_i) \
;         __builtin_amdgcn_global_load_lds((const unsigned*)((const char*)(gbase) + (voff)[_i]), (PG8_LAS unsigned*)(lds + (bufoff) + ldsw + _i * 8192), 16, 0, 0); } while (0)
; #define PG8_LDA(dst, b, h) do { _Pragma("unroll") for (int m = 0; m < 4; ++m) _Pragma("unroll") for (int k = 0; k < 2; ++k) dst[m][k] = *(const PG8_LAS bf16x8*)(lds + PG8_SA(b, h) + aoff + m * 2048 + k * 1024); } while (0)
; #define PG8_WAIT_V(n) asm volatile("s_waitcnt vmcnt(" #n ")" ::: "memory")
; #define PG8_BAR __builtin_amdgcn_s_barrier()
;     __device__ __forceinline__ void operator()(const f32x4 (&acc)[2][2][4][2], const Unit& u, int wr, int wc, int fr, int fq) const {
;     ...
;                 for (int bj = 0; bj < 2; ++bj) { f32x4 b0, b1;
;                     if (BF) { unpack8(*(const u32x4*)((const bf16_t*)base + off + bj * HALF), b0, b1); }
;                     else { b0 = *(const f32x4*)((const float*)base + off + bj * HALF); b1 = *(const f32x4*)((const float*)base + off + bj * HALF + 4); }
;                     *(u32x4*)(O + off + bj * HALF) = pack8(b0 + acc[ai][bj][m][0], b1 + acc[ai][bj][m][1]); } }
; template <class Epi, class Sched, bool ALIGN_EPI = false, bool SP2 = false>
; __device__ __forceinline__ void gemm_phase(PG8_LAS unsigned char* lds, const Gemm g, const Sched& S, const Epi& E, const int tid_in) {
;     ...
;             if constexpr (SP2) {
;             PG8_LDB(B0, 0, 0); PG8_LDB(B1, 0, 1); PG8_SCHED; PG8_LDA(At, 0, 0); PG8_STAGE(PG8_SA(1, 1), a1 + hstep, voffA);
;             PG8_WAIT_V(8); PG8_WAIT_L(0); PG8_BAR; PG8_MMA(0, 0, At, B0); PG8_MMA(0, 1, At, B1); PG8_BAR; PG8_SCHED;
;             PG8_LDA(At, 0, 1); PG8_STAGE(PG8_SB(0, 0), b2, voffB); PG8_STAGE(PG8_SB(0, 1), b2 + hstep, voffB); PG8_STAGE(PG8_SA(0, 0), a2, voffA);
;             PG8_WAIT_V(8); PG8_WAIT_L(0); PG8_BAR; PG8_MMA(1, 0, At, B0); PG8_MMA(1, 1, At, B1); PG8_BAR; PG8_SCHED;
.Lmy_ra_1:
	v_pk_add_f32 v[108:109], v[108:109], v[228:229]
	v_pk_add_f32 v[110:111], v[110:111], v[230:231]
	v_pk_add_f32 v[104:105], v[104:105], v[232:233]
	v_pk_add_f32 v[106:107], v[106:107], v[234:235]
	v_pk_add_f32 v[100:101], v[100:101], v[236:237]
	v_pk_add_f32 v[102:103], v[102:103], v[238:239]
	v_pk_add_f32 v[96:97], v[96:97], v[240:241]
	v_pk_add_f32 v[98:99], v[98:99], v[242:243]
	s_branch .Lmy_ra_done
.Lmy_ra_2:
	v_pk_add_f32 v[92:93], v[92:93], v[228:229]
	v_pk_add_f32 v[94:95], v[94:95], v[230:231]
	v_pk_add_f32 v[88:89], v[88:89], v[232:233]
	v_pk_add_f32 v[90:91], v[90:91], v[234:235]
	v_pk_add_f32 v[84:85], v[84:85], v[236:237]
	v_pk_add_f32 v[86:87], v[86:87], v[238:239]
	v_pk_add_f32 v[80:81], v[80:81], v[240:241]
	v_pk_add_f32 v[82:83], v[82:83], v[242:243]
	s_branch .Lmy_ra_done
.Lmy_ra_3:
	v_pk_add_f32 v[76:77], v[76:77], v[228:229]
	v_pk_add_f32 v[78:79], v[78:79], v[230:231]
	v_pk_add_f32 v[72:73], v[72:73], v[232:233]
	v_pk_add_f32 v[74:75], v[74:75], v[234:235]
	v_pk_add_f32 v[68:69], v[68:69], v[236:237]
	v_pk_add_f32 v[70:71], v[70:71], v[238:239]
	v_pk_add_f32 v[64:65], v[64:65], v[240:241]
	v_pk_add_f32 v[66:67], v[66:67], v[242:243]
	s_branch .Lmy_ra_done
.Lmy_ra_4:
	v_pk_add_f32 v[60:61], v[60:61], v[228:229]
	v_pk_add_f32 v[62:63], v[62:63], v[230:231]
	v_pk_add_f32 v[56:57], v[56:57], v[232:233]
	v_pk_add_f32 v[58:59], v[58:59], v[234:235]
	v_pk_add_f32 v[52:53], v[52:53], v[236:237]
	v_pk_add_f32 v[54:55], v[54:55], v[238:239]
	v_pk_add_f32 v[48:49], v[48:49], v[240:241]
	v_pk_add_f32 v[50:51], v[50:51], v[242:243]
	s_branch .Lmy_ra_done
.Lmy_ra_5:
	v_pk_add_f32 v[44:45], v[44:45], v[228:229]
	v_pk_add_f32 v[46:47], v[46:47], v[230:231]
	v_pk_add_f32 v[40:41], v[40:41], v[232:233]
	v_pk_add_f32 v[42:43], v[42:43], v[234:235]
	v_pk_add_f32 v[36:37], v[36:37], v[236:237]
	v_pk_add_f32 v[38:39], v[38:39], v[238:239]
	v_pk_add_f32 v[32:33], v[32:33], v[240:241]
	v_pk_add_f32 v[34:35], v[34:35], v[242:243]
	s_branch .Lmy_ra_done
.Lmy_ra_6:
	v_pk_add_f32 v[28:29], v[28:29], v[228:229]
	v_pk_add_f32 v[30:31], v[30:31], v[230:231]
	v_pk_add_f32 v[24:25], v[24:25], v[232:233]
	v_pk_add_f32 v[26:27], v[26:27], v[234:235]
	v_pk_add_f32 v[20:21], v[20:21], v[236:237]
	v_pk_add_f32 v[22:23], v[22:23], v[238:239]
	v_pk_add_f32 v[16:17], v[16:17], v[240:241]
	v_pk_add_f32 v[18:19], v[18:19], v[242:243]
.Lmy_ra_done:
	s_barrier
	s_setprio 1
	s_waitcnt lgkmcnt(0)
	v_mfma_f32_16x16x32_bf16 v[124:127], v[144:147], v[184:187], v[124:127]
	v_mfma_f32_16x16x32_bf16 v[120:123], v[160:163], v[184:187], v[120:123]
	v_mfma_f32_16x16x32_bf16 v[108:111], v[144:147], v[192:195], v[108:111]
	v_mfma_f32_16x16x32_bf16 v[104:107], v[160:163], v[192:195], v[104:107]
	v_mfma_f32_16x16x32_bf16 v[92:95], v[144:147], v[200:203], v[92:95]
	v_mfma_f32_16x16x32_bf16 v[88:91], v[160:163], v[200:203], v[88:91]
	v_mfma_f32_16x16x32_bf16 v[76:79], v[144:147], v[208:211], v[76:79]
	v_mfma_f32_16x16x32_bf16 v[72:75], v[160:163], v[208:211], v[72:75]
	v_mfma_f32_16x16x32_bf16 v[124:127], v[156:159], v[188:191], v[124:127]
	v_mfma_f32_16x16x32_bf16 v[120:123], v[164:167], v[188:191], v[120:123]
	v_mfma_f32_16x16x32_bf16 v[108:111], v[156:159], v[196:199], v[108:111]
	v_mfma_f32_16x16x32_bf16 v[104:107], v[164:167], v[196:199], v[104:107]
	v_mfma_f32_16x16x32_bf16 v[92:95], v[156:159], v[204:207], v[92:95]
	v_mfma_f32_16x16x32_bf16 v[88:91], v[164:167], v[204:207], v[88:91]
	v_mfma_f32_16x16x32_bf16 v[76:79], v[156:159], v[212:215], v[76:79]
	v_mfma_f32_16x16x32_bf16 v[72:75], v[164:167], v[212:215], v[72:75]
	s_setprio 0
	s_setprio 1
	v_mfma_f32_16x16x32_bf16 v[116:119], v[168:171], v[184:187], v[116:119]
	v_mfma_f32_16x16x32_bf16 v[112:115], v[176:179], v[184:187], v[112:115]
	v_mfma_f32_16x16x32_bf16 v[100:103], v[168:171], v[192:195], v[100:103]
	v_mfma_f32_16x16x32_bf16 v[96:99], v[176:179], v[192:195], v[96:99]
	v_mfma_f32_16x16x32_bf16 v[84:87], v[168:171], v[200:203], v[84:87]
	v_mfma_f32_16x16x32_bf16 v[80:83], v[176:179], v[200:203], v[80:83]
	v_mfma_f32_16x16x32_bf16 v[68:71], v[168:171], v[208:211], v[68:71]
	v_mfma_f32_16x16x32_bf16 v[64:67], v[176:179], v[208:211], v[64:67]
	v_mfma_f32_16x16x32_bf16 v[116:119], v[172:175], v[188:191], v[116:119]
	v_mfma_f32_16x16x32_bf16 v[112:115], v[180:183], v[188:191], v[112:115]
	v_mfma_f32_16x16x32_bf16 v[100:103], v[172:175], v[196:199], v[100:103]
	v_mfma_f32_16x16x32_bf16 v[96:99], v[180:183], v[196:199], v[96:99]
	v_mfma_f32_16x16x32_bf16 v[84:87], v[172:175], v[204:207], v[84:87]
	v_mfma_f32_16x16x32_bf16 v[80:83], v[180:183], v[204:207], v[80:83]
	v_mfma_f32_16x16x32_bf16 v[68:71], v[172:175], v[212:215], v[68:71]
	v_mfma_f32_16x16x32_bf16 v[64:67], v[180:183], v[212:215], v[64:67]
	s_setprio 0
	s_barrier
	s_add_i32 s63, s53, s43
	v_lshl_add_u64 v[148:149], s[36:37], 0, v[132:133]
	s_mov_b32 m0, s63
	ds_read_b128 v[184:187], v155 offset:16384
	ds_read_b128 v[188:191], v155 offset:17408
	ds_read_b128 v[192:195], v155 offset:18432
	ds_read_b128 v[196:199], v155 offset:19456
	ds_read_b128 v[200:203], v155 offset:20480
	ds_read_b128 v[204:207], v155 offset:21504
	ds_read_b128 v[208:211], v155 offset:22528
	ds_read_b128 v[212:215], v155 offset:23552
	global_load_lds_dwordx4 v[148:149], off
	s_add_i32 m0, s63, 0x2000
	s_add_u32 s64, s36, 0x40000
	v_lshl_add_u64 v[216:217], s[36:37], 0, v[128:129]
	s_addc_u32 s65, s37, 0
	s_add_i32 s63, s56, s43
	global_load_lds_dwordx4 v[216:217], off
	v_lshl_add_u64 v[218:219], s[64:65], 0, v[132:133]
	s_mov_b32 m0, s63
	v_lshl_add_u64 v[220:221], s[38:39], 0, v[130:131]
	global_load_lds_dwordx4 v[218:219], off
	v_lshl_add_u64 v[218:219], s[64:65], 0, v[128:129]
	s_add_i32 m0, s63, 0x2000
	s_nop 0
	global_load_lds_dwordx4 v[218:219], off
	v_lshl_add_u64 v[218:219], s[38:39], 0, v[134:135]
	s_mov_b32 m0, s35
	s_nop 0
	global_load_lds_dwordx4 v[218:219], off
	s_mov_b32 m0, s45
	s_nop 0
	global_load_lds_dwordx4 v[220:221], off
	s_waitcnt vmcnt(8)
	s_waitcnt lgkmcnt(0)
	global_load_dwordx4 v[228:231], v[224:225], off
	global_load_dwordx4 v[232:235], v[224:225], off offset:16
	global_load_dwordx4 v[236:239], v[224:225], off offset:512
	global_load_dwordx4 v[240:243], v[224:225], off offset:528
	s_mov_b32 s98, 0x10000
	s_cmp_eq_u32 s62, 4
	s_cselect_b32 s98, 0x50000, s98
	v_add_co_u32_e32 v224, vcc, s98, v224
	s_nop 1
	v_addc_co_u32_e32 v225, vcc, 0, v225, vcc
	s_barrier
; #define PG8_STAGE(bufoff, gbase, voff) do { _Pragma("unroll") for (int _i = 0; _i < 2; ++_i) \
;         __builtin_amdgcn_global_load_lds((const unsigned*)((const char*)(gbase) + (voff)[_i]), (PG8_LAS unsigned*)(lds + (bufoff) + ldsw + _i * 8192), 16, 0, 0); } while (0)
; #define PG8_LDA(dst, b, h) do { _Pragma("unroll") for (int m = 0; m < 4; ++m) _Pragma("unroll") for (int k = 0; k < 2; ++k) dst[m][k] = *(const PG8_LAS bf16x8*)(lds + PG8_SA(b, h) + aoff + m * 2048 + k * 1024); } while (0)
; #define PG8_LDB(dst, b, h) do { _Pragma("unroll") for (int n = 0; n < 2; ++n) _Pragma("unroll") for (int k = 0; k < 2; ++k) dst[n][k] = *(const PG8_LAS bf16x8*)(lds + PG8_SB(b, h) + boff + n * 2048 + k * 1024); } while (0)
; #define PG8_MMA(ai, bj, At, Bt) do { __builtin_amdgcn_s_setprio(1); _Pragma("unroll") for (int m = 0; m < 4; ++m) _Pragma("unroll") for (int n = 0; n < 2; ++n) _Pragma("unroll") for (int k = 0; k < 2; ++k) \
;         acc[ai][bj][m][n] = __builtin_amdgcn_mfma_f32_16x16x32_bf16(Bt[n][k], At[m][k], acc[ai][bj][m][n], 0, 0, 0); __builtin_amdgcn_s_setprio(0); } while (0)
; #define PG8_WAIT_V(n) asm volatile("s_waitcnt vmcnt(" #n ")" ::: "memory")
; #define PG8_WAIT_L(n) asm volatile("s_waitcnt lgkmcnt(" #n ")" ::: "memory")
; #define PG8_BAR __builtin_amdgcn_s_barrier()
; #define PG8_SCHED __builtin_amdgcn_sched_barrier(0)
; template <class Epi, class Sched, bool ALIGN_EPI = false, bool SP2 = false>
; __device__ __forceinline__ void gemm_phase(PG8_LAS unsigned char* lds, const Gemm g, const Sched& S, const Epi& E, const int tid_in) {
;     ...
;             PG8_WAIT_V(8); PG8_WAIT_L(0); PG8_BAR; PG8_MMA(1, 0, At, B0); PG8_MMA(1, 1, At, B1); PG8_BAR; PG8_SCHED;
;             PG8_LDB(B0, 1, 0); PG8_LDB(B1, 1, 1); PG8_SCHED; PG8_LDA(At, 1, 0); PG8_STAGE(PG8_SA(0, 1), a2 + hstep, voffA);
;             PG8_WAIT_V(8); PG8_WAIT_L(0); PG8_BAR; PG8_MMA(0, 0, At, B0); PG8_MMA(0, 1, At, B1); PG8_BAR; PG8_SCHED;
;             PG8_LDA(At, 1, 1); PG8_STAGE(PG8_SB(1, 0), b3, voffB); PG8_STAGE(PG8_SB(1, 1), b3 + hstep, voffB); PG8_STAGE(PG8_SA(1, 0), a3, voffA);
	s_setprio 1
	s_waitcnt lgkmcnt(0)
	v_mfma_f32_16x16x32_bf16 v[60:63], v[144:147], v[184:187], v[60:63]
	v_mfma_f32_16x16x32_bf16 v[56:59], v[160:163], v[184:187], v[56:59]
	v_mfma_f32_16x16x32_bf16 v[44:47], v[144:147], v[192:195], v[44:47]
	v_mfma_f32_16x16x32_bf16 v[40:43], v[160:163], v[192:195], v[40:43]
	v_mfma_f32_16x16x32_bf16 v[28:31], v[144:147], v[200:203], v[28:31]
	v_mfma_f32_16x16x32_bf16 v[24:27], v[160:163], v[200:203], v[24:27]
	v_mfma_f32_16x16x32_bf16 v[12:15], v[144:147], v[208:211], v[12:15]
	v_mfma_f32_16x16x32_bf16 v[8:11], v[160:163], v[208:211], v[8:11]
	v_mfma_f32_16x16x32_bf16 v[60:63], v[156:159], v[188:191], v[60:63]
	v_mfma_f32_16x16x32_bf16 v[56:59], v[164:167], v[188:191], v[56:59]
	v_mfma_f32_16x16x32_bf16 v[44:47], v[156:159], v[196:199], v[44:47]
	v_mfma_f32_16x16x32_bf16 v[40:43], v[164:167], v[196:199], v[40:43]
	v_mfma_f32_16x16x32_bf16 v[28:31], v[156:159], v[204:207], v[28:31]
	v_mfma_f32_16x16x32_bf16 v[24:27], v[164:167], v[204:207], v[24:27]
	v_mfma_f32_16x16x32_bf16 v[12:15], v[156:159], v[212:215], v[12:15]
	v_mfma_f32_16x16x32_bf16 v[8:11], v[164:167], v[212:215], v[8:11]
	s_setprio 0
	s_setprio 1
	v_mfma_f32_16x16x32_bf16 v[52:55], v[168:171], v[184:187], v[52:55]
	v_mfma_f32_16x16x32_bf16 v[48:51], v[176:179], v[184:187], v[48:51]
	v_mfma_f32_16x16x32_bf16 v[36:39], v[168:171], v[192:195], v[36:39]
	v_mfma_f32_16x16x32_bf16 v[32:35], v[176:179], v[192:195], v[32:35]
	v_mfma_f32_16x16x32_bf16 v[20:23], v[168:171], v[200:203], v[20:23]
	v_mfma_f32_16x16x32_bf16 v[16:19], v[176:179], v[200:203], v[16:19]
	v_mfma_f32_16x16x32_bf16 v[4:7], v[168:171], v[208:211], v[4:7]
	v_mfma_f32_16x16x32_bf16 v[0:3], v[176:179], v[208:211], v[0:3]
	v_mfma_f32_16x16x32_bf16 v[52:55], v[172:175], v[188:191], v[52:55]
	v_mfma_f32_16x16x32_bf16 v[48:51], v[180:183], v[188:191], v[48:51]
	v_mfma_f32_16x16x32_bf16 v[36:39], v[172:175], v[196:199], v[36:39]
	v_mfma_f32_16x16x32_bf16 v[32:35], v[180:183], v[196:199], v[32:35]
	v_mfma_f32_16x16x32_bf16 v[20:23], v[172:175], v[204:207], v[20:23]
	v_mfma_f32_16x16x32_bf16 v[16:19], v[180:183], v[204:207], v[16:19]
	v_mfma_f32_16x16x32_bf16 v[4:7], v[172:175], v[212:215], v[4:7]
	v_mfma_f32_16x16x32_bf16 v[0:3], v[180:183], v[212:215], v[0:3]
	s_setprio 0
	s_barrier
	s_add_i32 s63, 0, 0x18000
	s_add_i32 s64, 0, 0x1c000
	v_add_u32_e32 v164, s63, v151
	v_add_u32_e32 v180, s64, v151
	ds_read_b128 v[144:147], v164
	ds_read_b128 v[156:159], v164 offset:1024
	ds_read_b128 v[160:163], v164 offset:2048
	ds_read_b128 v[164:167], v164 offset:3072
	ds_read_b128 v[168:171], v180
	ds_read_b128 v[172:175], v180 offset:1024
	ds_read_b128 v[176:179], v180 offset:2048
	ds_read_b128 v[180:183], v180 offset:3072
	s_add_u32 s38, s38, 0x40000
	s_addc_u32 s39, s39, 0
	s_mov_b32 m0, s46
	v_lshl_add_u64 v[222:223], s[38:39], 0, v[134:135]
	ds_read_b128 v[184:187], v155 offset:32768
	ds_read_b128 v[188:191], v155 offset:33792
	ds_read_b128 v[192:195], v155 offset:34816
	ds_read_b128 v[196:199], v155 offset:35840
	ds_read_b128 v[200:203], v155 offset:36864
	ds_read_b128 v[204:207], v155 offset:37888
	ds_read_b128 v[208:211], v155 offset:38912
	ds_read_b128 v[212:215], v155 offset:39936
	global_load_lds_dwordx4 v[222:223], off
	v_lshl_add_u64 v[222:223], s[38:39], 0, v[130:131]
	s_mov_b32 m0, s47
	s_nop 0
	global_load_lds_dwordx4 v[222:223], off
	s_waitcnt vmcnt(12)
	s_waitcnt lgkmcnt(0)
	s_barrier
	s_setprio 1
	s_waitcnt lgkmcnt(0)
	v_mfma_f32_16x16x32_bf16 v[124:127], v[144:147], v[184:187], v[124:127]
	v_mfma_f32_16x16x32_bf16 v[120:123], v[160:163], v[184:187], v[120:123]
	v_mfma_f32_16x16x32_bf16 v[108:111], v[144:147], v[192:195], v[108:111]
	v_mfma_f32_16x16x32_bf16 v[104:107], v[160:163], v[192:195], v[104:107]
	v_mfma_f32_16x16x32_bf16 v[92:95], v[144:147], v[200:203], v[92:95]
	v_mfma_f32_16x16x32_bf16 v[88:91], v[160:163], v[200:203], v[88:91]
	v_mfma_f32_16x16x32_bf16 v[76:79], v[144:147], v[208:211], v[76:79]
	v_mfma_f32_16x16x32_bf16 v[72:75], v[160:163], v[208:211], v[72:75]
	v_mfma_f32_16x16x32_bf16 v[124:127], v[156:159], v[188:191], v[124:127]
	v_mfma_f32_16x16x32_bf16 v[120:123], v[164:167], v[188:191], v[120:123]
	v_mfma_f32_16x16x32_bf16 v[108:111], v[156:159], v[196:199], v[108:111]
	v_mfma_f32_16x16x32_bf16 v[104:107], v[164:167], v[196:199], v[104:107]
	v_mfma_f32_16x16x32_bf16 v[92:95], v[156:159], v[204:207], v[92:95]
	v_mfma_f32_16x16x32_bf16 v[88:91], v[164:167], v[204:207], v[88:91]
	v_mfma_f32_16x16x32_bf16 v[76:79], v[156:159], v[212:215], v[76:79]
	v_mfma_f32_16x16x32_bf16 v[72:75], v[164:167], v[212:215], v[72:75]
	s_setprio 0
	s_setprio 1
	v_mfma_f32_16x16x32_bf16 v[116:119], v[168:171], v[184:187], v[116:119]
	v_mfma_f32_16x16x32_bf16 v[112:115], v[176:179], v[184:187], v[112:115]
	v_mfma_f32_16x16x32_bf16 v[100:103], v[168:171], v[192:195], v[100:103]
	v_mfma_f32_16x16x32_bf16 v[96:99], v[176:179], v[192:195], v[96:99]
	v_mfma_f32_16x16x32_bf16 v[84:87], v[168:171], v[200:203], v[84:87]
	v_mfma_f32_16x16x32_bf16 v[80:83], v[176:179], v[200:203], v[80:83]
	v_mfma_f32_16x16x32_bf16 v[68:71], v[168:171], v[208:211], v[68:71]
	v_mfma_f32_16x16x32_bf16 v[64:67], v[176:179], v[208:211], v[64:67]
	v_mfma_f32_16x16x32_bf16 v[116:119], v[172:175], v[188:191], v[116:119]
	v_mfma_f32_16x16x32_bf16 v[112:115], v[180:183], v[188:191], v[112:115]
	v_mfma_f32_16x16x32_bf16 v[100:103], v[172:175], v[196:199], v[100:103]
	v_mfma_f32_16x16x32_bf16 v[96:99], v[180:183], v[196:199], v[96:99]
	v_mfma_f32_16x16x32_bf16 v[84:87], v[172:175], v[204:207], v[84:87]
	v_mfma_f32_16x16x32_bf16 v[80:83], v[180:183], v[204:207], v[80:83]
	v_mfma_f32_16x16x32_bf16 v[68:71], v[172:175], v[212:215], v[68:71]
	v_mfma_f32_16x16x32_bf16 v[64:67], v[180:183], v[212:215], v[64:67]
	s_setprio 0
	s_barrier
; #define PG8_STAGE(bufoff, gbase, voff) do { _Pragma("unroll") for (int _i = 0; _i < 2; ++_i) \
;         __builtin_amdgcn_global_load_lds((const unsigned*)((const char*)(gbase) + (voff)[_i]), (PG8_LAS unsigned*)(lds + (bufoff) + ldsw + _i * 8192), 16, 0, 0); } while (0)
; #define PG8_LDA(dst, b, h) do { _Pragma("unroll") for (int m = 0; m < 4; ++m) _Pragma("unroll") for (int k = 0; k < 2; ++k) dst[m][k] = *(const PG8_LAS bf16x8*)(lds + PG8_SA(b, h) + aoff + m * 2048 + k * 1024); } while (0)
; #define PG8_MMA(ai, bj, At, Bt) do { __builtin_amdgcn_s_setprio(1); _Pragma("unroll") for (int m = 0; m < 4; ++m) _Pragma("unroll") for (int n = 0; n < 2; ++n) _Pragma("unroll") for (int k = 0; k < 2; ++k) \
;         acc[ai][bj][m][n] = __builtin_amdgcn_mfma_f32_16x16x32_bf16(Bt[n][k], At[m][k], acc[ai][bj][m][n], 0, 0, 0); __builtin_amdgcn_s_setprio(0); } while (0)
; #define PG8_WAIT_V(n) asm volatile("s_waitcnt vmcnt(" #n ")" ::: "memory")
; #define PG8_WAIT_L(n) asm volatile("s_waitcnt lgkmcnt(" #n ")" ::: "memory")
; #define PG8_BAR __builtin_amdgcn_s_barrier()
; #define PG8_SCHED __builtin_amdgcn_sched_barrier(0)
; template <class Epi, class Sched, bool ALIGN_EPI = false, bool SP2 = false>
; __device__ __forceinline__ void gemm_phase(PG8_LAS unsigned char* lds, const Gemm g, const Sched& S, const Epi& E, const int tid_in) {
;     ...
;             PG8_WAIT_V(8); PG8_WAIT_L(0); PG8_BAR; PG8_MMA(0, 0, At, B0); PG8_MMA(0, 1, At, B1); PG8_BAR; PG8_SCHED;
;             PG8_LDA(At, 1, 1); PG8_STAGE(PG8_SB(1, 0), b3, voffB); PG8_STAGE(PG8_SB(1, 1), b3 + hstep, voffB); PG8_STAGE(PG8_SA(1, 0), a3, voffA);
;             PG8_WAIT_V(8); PG8_WAIT_L(0); PG8_BAR; PG8_MMA(1, 0, At, B0); PG8_MMA(1, 1, At, B1); PG8_BAR; PG8_SCHED;
	s_add_i32 s38, s63, s43
	v_lshl_add_u64 v[148:149], v[148:149], 0, s[12:13]
	s_mov_b32 m0, s38
	ds_read_b128 v[184:187], v155 offset:49152
	ds_read_b128 v[188:191], v155 offset:50176
	ds_read_b128 v[192:195], v155 offset:51200
	ds_read_b128 v[196:199], v155 offset:52224
	ds_read_b128 v[200:203], v155 offset:53248
	ds_read_b128 v[204:207], v155 offset:54272
	ds_read_b128 v[208:211], v155 offset:55296
	ds_read_b128 v[212:215], v155 offset:56320
	global_load_lds_dwordx4 v[148:149], off
	s_add_i32 m0, s38, 0x2000
	s_add_u32 s36, s36, 0x40080
	v_lshl_add_u64 v[148:149], v[216:217], 0, s[12:13]
	s_addc_u32 s37, s37, 0
	s_add_i32 s38, s64, s43
	global_load_lds_dwordx4 v[148:149], off
	v_lshl_add_u64 v[148:149], s[36:37], 0, v[132:133]
	s_mov_b32 m0, s38
	s_nop 0
	global_load_lds_dwordx4 v[148:149], off
	v_lshl_add_u64 v[148:149], s[36:37], 0, v[128:129]
	s_add_i32 m0, s38, 0x2000
	s_nop 0
	global_load_lds_dwordx4 v[148:149], off
	v_lshl_add_u64 v[148:149], v[218:219], 0, s[12:13]
	s_mov_b32 m0, s50
	s_nop 0
	global_load_lds_dwordx4 v[148:149], off
	v_lshl_add_u64 v[148:149], v[220:221], 0, s[12:13]
	s_mov_b32 m0, s51
	s_nop 0
	global_load_lds_dwordx4 v[148:149], off
	s_waitcnt vmcnt(12)
	s_waitcnt lgkmcnt(0)
	s_barrier
	s_setprio 1
	s_waitcnt lgkmcnt(0)
	v_mfma_f32_16x16x32_bf16 v[60:63], v[144:147], v[184:187], v[60:63]
	v_mfma_f32_16x16x32_bf16 v[56:59], v[160:163], v[184:187], v[56:59]
	v_mfma_f32_16x16x32_bf16 v[44:47], v[144:147], v[192:195], v[44:47]
	v_mfma_f32_16x16x32_bf16 v[40:43], v[160:163], v[192:195], v[40:43]
	v_mfma_f32_16x16x32_bf16 v[28:31], v[144:147], v[200:203], v[28:31]
	v_mfma_f32_16x16x32_bf16 v[24:27], v[160:163], v[200:203], v[24:27]
	v_mfma_f32_16x16x32_bf16 v[12:15], v[144:147], v[208:211], v[12:15]
	v_mfma_f32_16x16x32_bf16 v[8:11], v[160:163], v[208:211], v[8:11]
	v_mfma_f32_16x16x32_bf16 v[60:63], v[156:159], v[188:191], v[60:63]
	v_mfma_f32_16x16x32_bf16 v[56:59], v[164:167], v[188:191], v[56:59]
	v_mfma_f32_16x16x32_bf16 v[44:47], v[156:159], v[196:199], v[44:47]
	v_mfma_f32_16x16x32_bf16 v[40:43], v[164:167], v[196:199], v[40:43]
	v_mfma_f32_16x16x32_bf16 v[28:31], v[156:159], v[204:207], v[28:31]
	v_mfma_f32_16x16x32_bf16 v[24:27], v[164:167], v[204:207], v[24:27]
	v_mfma_f32_16x16x32_bf16 v[12:15], v[156:159], v[212:215], v[12:15]
	v_mfma_f32_16x16x32_bf16 v[8:11], v[164:167], v[212:215], v[8:11]
	s_setprio 0
	s_setprio 1
	v_mfma_f32_16x16x32_bf16 v[52:55], v[168:171], v[184:187], v[52:55]
	v_mfma_f32_16x16x32_bf16 v[48:51], v[176:179], v[184:187], v[48:51]
	v_mfma_f32_16x16x32_bf16 v[36:39], v[168:171], v[192:195], v[36:39]
	v_mfma_f32_16x16x32_bf16 v[32:35], v[176:179], v[192:195], v[32:35]
	v_mfma_f32_16x16x32_bf16 v[20:23], v[168:171], v[200:203], v[20:23]
	v_mfma_f32_16x16x32_bf16 v[16:19], v[176:179], v[200:203], v[16:19]
	v_mfma_f32_16x16x32_bf16 v[4:7], v[168:171], v[208:211], v[4:7]
	v_mfma_f32_16x16x32_bf16 v[0:3], v[176:179], v[208:211], v[0:3]
	v_mfma_f32_16x16x32_bf16 v[52:55], v[172:175], v[188:191], v[52:55]
	v_mfma_f32_16x16x32_bf16 v[48:51], v[180:183], v[188:191], v[48:51]
	v_mfma_f32_16x16x32_bf16 v[36:39], v[172:175], v[196:199], v[36:39]
	v_mfma_f32_16x16x32_bf16 v[32:35], v[180:183], v[196:199], v[32:35]
	v_mfma_f32_16x16x32_bf16 v[20:23], v[172:175], v[204:207], v[20:23]
	v_mfma_f32_16x16x32_bf16 v[16:19], v[180:183], v[204:207], v[16:19]
	v_mfma_f32_16x16x32_bf16 v[4:7], v[172:175], v[212:215], v[4:7]
	v_mfma_f32_16x16x32_bf16 v[0:3], v[180:183], v[212:215], v[0:3]
	s_setprio 0
	s_barrier
	s_add_i32 s62, s62, 2
	s_add_u32 s0, s0, 0x100
	s_addc_u32 s1, s1, 0
	s_add_u32 s60, s60, 0x100
	s_addc_u32 s61, s61, 0
	s_cmp_gt_u32 s62, 13
	s_cbranch_scc0 .LBB0_316
	s_and_b64 vcc, exec, s[14:15]
	s_cbranch_vccz .LBB0_319
	s_barrier
; __device__ __forceinline__ u32x4 pack8(const f32x4 a, const f32x4 b) { u32x4 w; w.x = cvt_pk_bf16(a[0], a[1]); w.y = cvt_pk_bf16(a[2], a[3]); w.z = cvt_pk_bf16(b[0], b[1]); w.w = cvt_pk_bf16(b[2], b[3]); return w; }
; __device__ __forceinline__ void unpack8(const u32x4 w, f32x4& a, f32x4& b) { a = (f32x4){bflo(w.x), bfhi(w.x), bflo(w.y), bfhi(w.y)}; b = (f32x4){bflo(w.z), bfhi(w.z), bflo(w.w), bfhi(w.w)}; }
;     __device__ __forceinline__ void operator()(const f32x4 (&acc)[2][2][4][2], const Unit& u, int wr, int wc, int fr, int fq) const {
;         const int row0 = u.pm * BM + wr * 64 + fr, col0 = u.pn * BM + wc * 32 + 8 * fq;
; #pragma unroll
;         for (int ai = 0; ai < 2; ++ai)
; #pragma unroll
;             for (int m = 0; m < 4; ++m) { const size_t off = (size_t)(row0 + ai * HALF + m * 16) * 1024 + col0;
; #pragma unroll
;                 for (int bj = 0; bj < 2; ++bj) { f32x4 b0, b1;
;                     if (BF) { unpack8(*(const u32x4*)((const bf16_t*)base + off + bj * HALF), b0, b1); }
;                     else { b0 = *(const f32x4*)((const float*)base + off + bj * HALF); b1 = *(const f32x4*)((const float*)base + off + bj * HALF + 4); }
;                     *(u32x4*)(O + off + bj * HALF) = pack8(b0 + acc[ai][bj][m][0], b1 + acc[ai][bj][m][1]); } }
.LBB0_319:
	v_lshl_add_u32 v148, s34, 8, v150
	v_lshl_or_b32 v146, s57, 8, v152
	v_ashrrev_i32_e32 v149, 31, v148
	v_ashrrev_i32_e32 v147, 31, v146
	v_lshlrev_b64 v[144:145], 10, v[148:149]
	v_lshl_add_u64 v[144:145], v[144:145], 0, v[146:147]
	v_lshl_add_u64 v[166:167], v[144:145], 1, s[10:11]
	s_mov_b64 s[0:1], -1
	v_mov_b32_e32 v248, 0x8000
	v_mov_b32_e32 v249, 0
	v_lshl_add_u64 v[168:169], v[248:249], 0, v[166:167]
	v_lshl_add_u64 v[170:171], v[248:249], 1, v[166:167]
	v_lshl_add_u64 v[172:173], v[248:249], 1, v[168:169]
	v_lshl_add_u64 v[174:175], v[248:249], 3, v[166:167]
	v_lshl_add_u64 v[176:177], v[248:249], 0, v[174:175]
	v_lshl_add_u64 v[178:179], v[248:249], 1, v[174:175]
	v_lshl_add_u64 v[180:181], v[248:249], 1, v[176:177]
	s_waitcnt vmcnt(0)
	v_pk_add_f32 v[12:13], v[12:13], v[228:229]
	v_pk_add_f32 v[14:15], v[14:15], v[230:231]
	v_pk_add_f32 v[8:9], v[8:9], v[232:233]
	v_pk_add_f32 v[10:11], v[10:11], v[234:235]
	v_pk_add_f32 v[4:5], v[4:5], v[236:237]
	v_pk_add_f32 v[6:7], v[6:7], v[238:239]
	v_pk_add_f32 v[0:1], v[0:1], v[240:241]
	v_pk_add_f32 v[2:3], v[2:3], v[242:243]
	v_cvt_pk_bf16_f32 v124, v124, v125
	v_cvt_pk_bf16_f32 v125, v126, v127
	v_cvt_pk_bf16_f32 v126, v120, v121
	v_cvt_pk_bf16_f32 v127, v122, v123
	global_store_dwordx4 v[166:167], v[124:127], off
	v_cvt_pk_bf16_f32 v116, v116, v117
	v_cvt_pk_bf16_f32 v117, v118, v119
	v_cvt_pk_bf16_f32 v118, v112, v113
	v_cvt_pk_bf16_f32 v119, v114, v115
	global_store_dwordx4 v[166:167], v[116:119], off offset:256
	v_cvt_pk_bf16_f32 v108, v108, v109
	v_cvt_pk_bf16_f32 v109, v110, v111
	v_cvt_pk_bf16_f32 v110, v104, v105
	v_cvt_pk_bf16_f32 v111, v106, v107
	global_store_dwordx4 v[168:169], v[108:111], off
	v_cvt_pk_bf16_f32 v100, v100, v101
	v_cvt_pk_bf16_f32 v101, v102, v103
	v_cvt_pk_bf16_f32 v102, v96, v97
	v_cvt_pk_bf16_f32 v103, v98, v99
	global_store_dwordx4 v[168:169], v[100:103], off offset:256
	v_cvt_pk_bf16_f32 v92, v92, v93
	v_cvt_pk_bf16_f32 v93, v94, v95
	v_cvt_pk_bf16_f32 v94, v88, v89
	v_cvt_pk_bf16_f32 v95, v90, v91
	global_store_dwordx4 v[170:171], v[92:95], off
	v_cvt_pk_bf16_f32 v84, v84, v85
	v_cvt_pk_bf16_f32 v85, v86, v87
	v_cvt_pk_bf16_f32 v86, v80, v81
	v_cvt_pk_bf16_f32 v87, v82, v83
	global_store_dwordx4 v[170:171], v[84:87], off offset:256
	v_cvt_pk_bf16_f32 v76, v76, v77
	v_cvt_pk_bf16_f32 v77, v78, v79
	v_cvt_pk_bf16_f32 v78, v72, v73
	v_cvt_pk_bf16_f32 v79, v74, v75
	global_store_dwordx4 v[172:173], v[76:79], off
	v_cvt_pk_bf16_f32 v68, v68, v69
	v_cvt_pk_bf16_f32 v69, v70, v71
	v_cvt_pk_bf16_f32 v70, v64, v65
	v_cvt_pk_bf16_f32 v71, v66, v67
	global_store_dwordx4 v[172:173], v[68:71], off offset:256
	v_cvt_pk_bf16_f32 v60, v60, v61
	v_cvt_pk_bf16_f32 v61, v62, v63
	v_cvt_pk_bf16_f32 v62, v56, v57
	v_cvt_pk_bf16_f32 v63, v58, v59
	global_store_dwordx4 v[174:175], v[60:63], off
	v_cvt_pk_bf16_f32 v52, v52, v53
	v_cvt_pk_bf16_f32 v53, v54, v55
	v_cvt_pk_bf16_f32 v54, v48, v49
	v_cvt_pk_bf16_f32 v55, v50, v51
	global_store_dwordx4 v[174:175], v[52:55], off offset:256
	v_cvt_pk_bf16_f32 v44, v44, v45
	v_cvt_pk_bf16_f32 v45, v46, v47
	v_cvt_pk_bf16_f32 v46, v40, v41
	v_cvt_pk_bf16_f32 v47, v42, v43
	global_store_dwordx4 v[176:177], v[44:47], off
	v_cvt_pk_bf16_f32 v36, v36, v37
	v_cvt_pk_bf16_f32 v37, v38, v39
	v_cvt_pk_bf16_f32 v38, v32, v33
	v_cvt_pk_bf16_f32 v39, v34, v35
	global_store_dwordx4 v[176:177], v[36:39], off offset:256
	v_cvt_pk_bf16_f32 v28, v28, v29
	v_cvt_pk_bf16_f32 v29, v30, v31
	v_cvt_pk_bf16_f32 v30, v24, v25
	v_cvt_pk_bf16_f32 v31, v26, v27
	global_store_dwordx4 v[178:179], v[28:31], off
	v_cvt_pk_bf16_f32 v20, v20, v21
	v_cvt_pk_bf16_f32 v21, v22, v23
	v_cvt_pk_bf16_f32 v22, v16, v17
	v_cvt_pk_bf16_f32 v23, v18, v19
	global_store_dwordx4 v[178:179], v[20:23], off offset:256
	v_cvt_pk_bf16_f32 v12, v12, v13
	v_cvt_pk_bf16_f32 v13, v14, v15
	v_cvt_pk_bf16_f32 v14, v8, v9
	v_cvt_pk_bf16_f32 v15, v10, v11
	global_store_dwordx4 v[180:181], v[12:15], off
	v_cvt_pk_bf16_f32 v4, v4, v5
	v_cvt_pk_bf16_f32 v5, v6, v7
	v_cvt_pk_bf16_f32 v6, v0, v1
	v_cvt_pk_bf16_f32 v7, v2, v3
	global_store_dwordx4 v[180:181], v[4:7], off offset:256
	s_andn2_b64 vcc, exec, s[2:3]
	s_cbranch_vccnz .LBB0_308
	s_andn2_b64 vcc, exec, s[8:9]
	s_cbranch_vccnz .LBB0_307
	s_barrier
	s_branch .LBB0_307
